# v54 + P1 V-tile LayerNorm partials: (sum,sumsq) xor-16/xor-32 reduction via permlane16/32 swaps instead of two serialized ds_bpermute pairs per row group
# speedup vs baseline: 1.0079x; 1.0079x over previous
.LBB0_225:
	v_mov_b32_e32 v169, v168
	v_pk_mul_f32 v[116:117], v[116:117], v[168:169]
	v_mov_b32_e32 v120, v168
	v_and_b32_e32 v123, 0x7fffffff, v117
	v_and_b32_e32 v122, 0x7fffffff, v116
	v_pk_fma_f32 v[122:123], v[122:123], s[26:27], 1.0 op_sel_hi:[1,0,0]
	v_mov_b32_e32 v121, v168
	v_rcp_f32_e32 v122, v122
	v_rcp_f32_e32 v123, v123
	v_pk_mul_f32 v[118:119], v[118:119], v[120:121]
	v_pk_mul_f32 v[114:115], v[114:115], v[120:121]
	v_pk_mul_f32 v[112:113], v[112:113], v[168:169]
	v_mov_b64_e32 v[120:121], s[30:31]
	v_pk_mul_f32 v[168:169], v[116:117], v[116:117]
	v_pk_fma_f32 v[126:127], v[122:123], s[28:29], v[120:121] op_sel_hi:[1,0,0]
	v_pk_mul_f32 v[168:169], v[168:169], s[40:41] op_sel_hi:[1,0]
	v_pk_fma_f32 v[126:127], v[122:123], v[126:127], s[34:35] op_sel_hi:[1,1,0]
	v_exp_f32_e32 v168, v168
	v_exp_f32_e32 v169, v169
	v_pk_fma_f32 v[126:127], v[122:123], v[126:127], s[36:37] op_sel_hi:[1,1,0]
	v_and_b32_e32 v197, 0x7fffffff, v119
	v_and_b32_e32 v196, 0x7fffffff, v118
	v_pk_fma_f32 v[126:127], v[122:123], v[126:127], s[38:39] op_sel_hi:[1,1,0]
	v_pk_fma_f32 v[196:197], v[196:197], s[26:27], 1.0 op_sel_hi:[1,0,0]
	v_pk_mul_f32 v[122:123], v[122:123], v[126:127]
	v_rcp_f32_e32 v196, v196
	v_rcp_f32_e32 v197, v197
	v_pk_mul_f32 v[122:123], v[168:169], v[122:123]
	v_cmp_gt_f32_e32 vcc, 0, v116
	v_pk_mul_f32 v[168:169], v[116:117], v[122:123]
	v_pk_fma_f32 v[122:123], v[116:117], v[122:123], v[116:117] neg_lo:[1,0,0] neg_hi:[1,0,0]
	v_pk_mul_f32 v[126:127], v[118:119], v[118:119]
	v_cndmask_b32_e32 v137, v122, v168, vcc
	v_cmp_gt_f32_e32 vcc, 0, v117
	v_pk_fma_f32 v[116:117], v[196:197], s[28:29], v[120:121] op_sel_hi:[1,0,0]
	s_lshl_b32 s8, s20, 3
	v_cndmask_b32_e32 v168, v123, v169, vcc
	v_pk_mul_f32 v[122:123], v[126:127], s[40:41] op_sel_hi:[1,0]
	v_pk_fma_f32 v[116:117], v[196:197], v[116:117], s[34:35] op_sel_hi:[1,1,0]
	v_exp_f32_e32 v122, v122
	v_exp_f32_e32 v123, v123
	v_pk_fma_f32 v[116:117], v[196:197], v[116:117], s[36:37] op_sel_hi:[1,1,0]
	v_and_b32_e32 v127, 0x7fffffff, v113
	v_and_b32_e32 v126, 0x7fffffff, v112
	v_pk_fma_f32 v[116:117], v[196:197], v[116:117], s[38:39] op_sel_hi:[1,1,0]
	v_pk_fma_f32 v[126:127], v[126:127], s[26:27], 1.0 op_sel_hi:[1,0,0]
	v_pk_mul_f32 v[116:117], v[196:197], v[116:117]
	v_rcp_f32_e32 v126, v126
	v_rcp_f32_e32 v127, v127
	v_pk_mul_f32 v[116:117], v[122:123], v[116:117]
	v_cmp_gt_f32_e32 vcc, 0, v118
	v_pk_mul_f32 v[122:123], v[118:119], v[116:117]
	v_pk_fma_f32 v[116:117], v[118:119], v[116:117], v[118:119] neg_lo:[1,0,0] neg_hi:[1,0,0]
	s_or_b32 s50, s8, s62
	v_cndmask_b32_e32 v169, v116, v122, vcc
	v_cmp_gt_f32_e32 vcc, 0, v119
	v_pk_mul_f32 v[118:119], v[112:113], v[112:113]
	s_ashr_i32 s51, s50, 31
	v_cndmask_b32_e32 v195, v117, v123, vcc
	v_pk_fma_f32 v[116:117], v[126:127], s[28:29], v[120:121] op_sel_hi:[1,0,0]
	v_pk_mul_f32 v[118:119], v[118:119], s[40:41] op_sel_hi:[1,0]
	v_pk_fma_f32 v[116:117], v[126:127], v[116:117], s[34:35] op_sel_hi:[1,1,0]
	v_exp_f32_e32 v118, v118
	v_pk_fma_f32 v[116:117], v[126:127], v[116:117], s[36:37] op_sel_hi:[1,1,0]
	v_exp_f32_e32 v119, v119
	v_pk_fma_f32 v[116:117], v[126:127], v[116:117], s[38:39] op_sel_hi:[1,1,0]
	v_cmp_gt_f32_e32 vcc, 0, v112
	v_pk_mul_f32 v[116:117], v[126:127], v[116:117]
	v_and_b32_e32 v127, 0x7fffffff, v115
	v_and_b32_e32 v126, 0x7fffffff, v114
	v_pk_fma_f32 v[126:127], v[126:127], s[26:27], 1.0 op_sel_hi:[1,0,0]
	v_pk_mul_f32 v[116:117], v[118:119], v[116:117]
	v_rcp_f32_e32 v126, v126
	v_rcp_f32_e32 v127, v127
	v_pk_mul_f32 v[118:119], v[112:113], v[116:117]
	v_pk_fma_f32 v[116:117], v[112:113], v[116:117], v[112:113] neg_lo:[1,0,0] neg_hi:[1,0,0]
	v_pk_mul_f32 v[122:123], v[114:115], v[114:115]
	v_cndmask_b32_e32 v118, v116, v118, vcc
	v_cmp_gt_f32_e32 vcc, 0, v113
	v_pk_fma_f32 v[112:113], v[126:127], s[28:29], v[120:121] op_sel_hi:[1,0,0]
	s_nop 0
	v_cndmask_b32_e32 v119, v117, v119, vcc
	v_pk_mul_f32 v[116:117], v[122:123], s[40:41] op_sel_hi:[1,0]
	v_pk_fma_f32 v[112:113], v[126:127], v[112:113], s[34:35] op_sel_hi:[1,1,0]
	v_exp_f32_e32 v116, v116
	v_exp_f32_e32 v117, v117
	v_pk_fma_f32 v[112:113], v[126:127], v[112:113], s[36:37] op_sel_hi:[1,1,0]
	v_cmp_gt_f32_e32 vcc, 0, v114
	v_pk_fma_f32 v[112:113], v[126:127], v[112:113], s[38:39] op_sel_hi:[1,1,0]
	s_nop 0
	v_pk_mul_f32 v[112:113], v[126:127], v[112:113]
	s_nop 0
	v_pk_mul_f32 v[112:113], v[116:117], v[112:113]
	s_nop 0
	v_pk_mul_f32 v[116:117], v[114:115], v[112:113]
	v_pk_fma_f32 v[112:113], v[114:115], v[112:113], v[114:115] neg_lo:[1,0,0] neg_hi:[1,0,0]
	s_nop 0
	v_cndmask_b32_e32 v116, v112, v116, vcc
	v_cmp_gt_f32_e32 vcc, 0, v115
	v_cvt_pk_bf16_f32 v112, v137, v168
	s_nop 1
	v_cndmask_b32_e32 v115, v113, v117, vcc
	v_cvt_pk_bf16_f32 v113, v169, v195
	v_cvt_pk_bf16_f32 v114, v118, v119
	v_cvt_pk_bf16_f32 v115, v116, v115
	v_cndmask_b32_e64 v116, 0, 1, s[10:11]
	v_cmp_ne_u32_e64 s[8:9], 1, v116
	s_andn2_b64 vcc, exec, s[10:11]
	global_store_dwordx4 v[166:167], v[112:115], off offset:256
	s_cbranch_vccnz .LBB0_229
	v_lshlrev_b32_e32 v116, 16, v112
	v_and_b32_e32 v112, 0xffff0000, v112
	v_lshlrev_b32_e32 v118, 16, v113
	v_and_b32_e32 v120, 0xffff0000, v113
	v_lshlrev_b32_e32 v122, 16, v114
	v_and_b32_e32 v114, 0xffff0000, v114
	v_lshlrev_b32_e32 v126, 16, v115
	v_and_b32_e32 v166, 0xffff0000, v115
	v_mul_f32_e32 v117, v116, v116
	v_mul_f32_e32 v113, v112, v112
	v_mul_f32_e32 v119, v118, v118
	v_mul_f32_e32 v121, v120, v120
	v_mul_f32_e32 v123, v122, v122
	v_mul_f32_e32 v115, v114, v114
	v_mul_f32_e32 v127, v126, v126
	v_mul_f32_e32 v167, v166, v166
	v_pk_add_f32 v[112:113], v[116:117], v[112:113]
	v_pk_add_f32 v[116:117], v[118:119], v[120:121]
	v_pk_add_f32 v[114:115], v[122:123], v[114:115]
	v_pk_add_f32 v[112:113], v[112:113], v[116:117]
	v_pk_add_f32 v[116:117], v[126:127], v[166:167]
	s_nop 0
	v_pk_add_f32 v[114:115], v[114:115], v[116:117]
	s_nop 0
	v_pk_add_f32 v[112:113], v[112:113], v[114:115]
	s_nop 0
	v_pk_add_f32 v[112:113], v[124:125], v[112:113]
	s_nop 0
	v_mov_b32_e32 v114, v112
	v_mov_b32_e32 v115, v113
	s_nop 0
	v_permlane16_swap_b32_e32 v112, v114
	v_permlane16_swap_b32_e32 v113, v115
	v_pk_add_f32 v[112:113], v[112:113], v[114:115]
	s_nop 0
	v_mov_b32_e32 v114, v112
	v_mov_b32_e32 v115, v113
	s_nop 0
	v_permlane32_swap_b32_e32 v112, v114
	v_permlane32_swap_b32_e32 v113, v115
	v_pk_add_f32 v[112:113], v[112:113], v[114:115]
	s_and_saveexec_b64 s[10:11], s[4:5]
	s_cbranch_execz .LBB0_228
	v_lshlrev_b64 v[116:117], 8, v[164:165]
	v_lshl_add_u64 v[116:117], s[16:17], 0, v[116:117]
	v_lshl_add_u64 v[116:117], s[50:51], 2, v[116:117]
	global_store_dwordx2 v[116:117], v[112:113], off

.LBB0_231:
	v_mov_b32_e32 v115, v114
	v_pk_mul_f32 v[100:101], v[100:101], v[114:115]
	v_mov_b32_e32 v104, v114
	v_and_b32_e32 v107, 0x7fffffff, v101
	v_and_b32_e32 v106, 0x7fffffff, v100
	v_pk_fma_f32 v[106:107], v[106:107], s[26:27], 1.0 op_sel_hi:[1,0,0]
	v_mov_b32_e32 v105, v114
	v_rcp_f32_e32 v106, v106
	v_rcp_f32_e32 v107, v107
	v_pk_mul_f32 v[102:103], v[102:103], v[104:105]
	v_pk_mul_f32 v[98:99], v[98:99], v[104:105]
	v_pk_mul_f32 v[96:97], v[96:97], v[114:115]
	v_mov_b64_e32 v[104:105], s[30:31]
	v_pk_mul_f32 v[114:115], v[100:101], v[100:101]
	v_pk_fma_f32 v[110:111], v[106:107], s[28:29], v[104:105] op_sel_hi:[1,0,0]
	v_pk_mul_f32 v[114:115], v[114:115], s[40:41] op_sel_hi:[1,0]
	v_pk_fma_f32 v[110:111], v[106:107], v[110:111], s[34:35] op_sel_hi:[1,1,0]
	v_exp_f32_e32 v114, v114
	v_exp_f32_e32 v115, v115
	v_pk_fma_f32 v[110:111], v[106:107], v[110:111], s[36:37] op_sel_hi:[1,1,0]
	v_and_b32_e32 v117, 0x7fffffff, v103
	v_and_b32_e32 v116, 0x7fffffff, v102
	v_pk_fma_f32 v[110:111], v[106:107], v[110:111], s[38:39] op_sel_hi:[1,1,0]
	v_pk_fma_f32 v[116:117], v[116:117], s[26:27], 1.0 op_sel_hi:[1,0,0]
	v_pk_mul_f32 v[106:107], v[106:107], v[110:111]
	v_rcp_f32_e32 v116, v116
	v_rcp_f32_e32 v117, v117
	v_pk_mul_f32 v[106:107], v[114:115], v[106:107]
	v_cmp_gt_f32_e32 vcc, 0, v100
	v_pk_mul_f32 v[114:115], v[100:101], v[106:107]
	v_pk_fma_f32 v[106:107], v[100:101], v[106:107], v[100:101] neg_lo:[1,0,0] neg_hi:[1,0,0]
	v_pk_mul_f32 v[110:111], v[102:103], v[102:103]
	v_cndmask_b32_e32 v114, v106, v114, vcc
	v_cmp_gt_f32_e32 vcc, 0, v101
	v_pk_fma_f32 v[100:101], v[116:117], s[28:29], v[104:105] op_sel_hi:[1,0,0]
	s_nop 0
	v_cndmask_b32_e32 v115, v107, v115, vcc
	v_pk_mul_f32 v[106:107], v[110:111], s[40:41] op_sel_hi:[1,0]
	v_pk_fma_f32 v[100:101], v[116:117], v[100:101], s[34:35] op_sel_hi:[1,1,0]
	v_exp_f32_e32 v106, v106
	v_exp_f32_e32 v107, v107
	v_pk_fma_f32 v[100:101], v[116:117], v[100:101], s[36:37] op_sel_hi:[1,1,0]
	v_and_b32_e32 v111, 0x7fffffff, v97
	v_and_b32_e32 v110, 0x7fffffff, v96
	v_pk_fma_f32 v[100:101], v[116:117], v[100:101], s[38:39] op_sel_hi:[1,1,0]
	v_pk_fma_f32 v[110:111], v[110:111], s[26:27], 1.0 op_sel_hi:[1,0,0]
	v_pk_mul_f32 v[100:101], v[116:117], v[100:101]
	v_rcp_f32_e32 v110, v110
	v_rcp_f32_e32 v111, v111
	v_pk_mul_f32 v[100:101], v[106:107], v[100:101]
	v_cmp_gt_f32_e32 vcc, 0, v102
	v_pk_mul_f32 v[106:107], v[102:103], v[100:101]
	v_pk_fma_f32 v[100:101], v[102:103], v[100:101], v[102:103] neg_lo:[1,0,0] neg_hi:[1,0,0]
	s_nop 0
	v_cndmask_b32_e32 v116, v100, v106, vcc
	v_cmp_gt_f32_e32 vcc, 0, v103
	v_pk_mul_f32 v[102:103], v[96:97], v[96:97]
	s_nop 0
	v_cndmask_b32_e32 v117, v101, v107, vcc
	v_pk_fma_f32 v[100:101], v[110:111], s[28:29], v[104:105] op_sel_hi:[1,0,0]
	v_pk_mul_f32 v[102:103], v[102:103], s[40:41] op_sel_hi:[1,0]
	v_pk_fma_f32 v[100:101], v[110:111], v[100:101], s[34:35] op_sel_hi:[1,1,0]
	v_exp_f32_e32 v102, v102
	v_pk_fma_f32 v[100:101], v[110:111], v[100:101], s[36:37] op_sel_hi:[1,1,0]
	v_exp_f32_e32 v103, v103
	v_pk_fma_f32 v[100:101], v[110:111], v[100:101], s[38:39] op_sel_hi:[1,1,0]
	v_cmp_gt_f32_e32 vcc, 0, v96
	v_pk_mul_f32 v[100:101], v[110:111], v[100:101]
	v_and_b32_e32 v111, 0x7fffffff, v99
	v_and_b32_e32 v110, 0x7fffffff, v98
	v_pk_fma_f32 v[110:111], v[110:111], s[26:27], 1.0 op_sel_hi:[1,0,0]
	v_pk_mul_f32 v[100:101], v[102:103], v[100:101]
	v_rcp_f32_e32 v110, v110
	v_rcp_f32_e32 v111, v111
	v_pk_mul_f32 v[102:103], v[96:97], v[100:101]
	v_pk_fma_f32 v[100:101], v[96:97], v[100:101], v[96:97] neg_lo:[1,0,0] neg_hi:[1,0,0]
	v_pk_mul_f32 v[106:107], v[98:99], v[98:99]
	v_cndmask_b32_e32 v102, v100, v102, vcc
	v_cmp_gt_f32_e32 vcc, 0, v97
	v_pk_fma_f32 v[96:97], v[110:111], s[28:29], v[104:105] op_sel_hi:[1,0,0]
	s_nop 0
	v_cndmask_b32_e32 v103, v101, v103, vcc
	v_pk_mul_f32 v[100:101], v[106:107], s[40:41] op_sel_hi:[1,0]
	v_pk_fma_f32 v[96:97], v[110:111], v[96:97], s[34:35] op_sel_hi:[1,1,0]
	v_exp_f32_e32 v100, v100
	v_exp_f32_e32 v101, v101
	v_pk_fma_f32 v[96:97], v[110:111], v[96:97], s[36:37] op_sel_hi:[1,1,0]
	v_cmp_gt_f32_e32 vcc, 0, v98
	v_pk_fma_f32 v[96:97], v[110:111], v[96:97], s[38:39] op_sel_hi:[1,1,0]
	s_nop 0
	v_pk_mul_f32 v[96:97], v[110:111], v[96:97]
	s_nop 0
	v_pk_mul_f32 v[96:97], v[100:101], v[96:97]
	s_nop 0
	v_pk_mul_f32 v[100:101], v[98:99], v[96:97]
	v_pk_fma_f32 v[96:97], v[98:99], v[96:97], v[98:99] neg_lo:[1,0,0] neg_hi:[1,0,0]
	s_nop 0
	v_cndmask_b32_e32 v100, v96, v100, vcc
	v_cmp_gt_f32_e32 vcc, 0, v99
	v_cvt_pk_bf16_f32 v96, v114, v115
	s_nop 1
	v_cndmask_b32_e32 v99, v97, v101, vcc
	s_and_b64 vcc, exec, s[8:9]
	v_cvt_pk_bf16_f32 v97, v116, v117
	v_cvt_pk_bf16_f32 v98, v102, v103
	v_cvt_pk_bf16_f32 v99, v100, v99
	global_store_dwordx4 v[112:113], v[96:99], off offset:256
	s_cbranch_vccnz .LBB0_235
	v_lshlrev_b32_e32 v100, 16, v96
	v_and_b32_e32 v96, 0xffff0000, v96
	v_lshlrev_b32_e32 v102, 16, v97
	v_and_b32_e32 v104, 0xffff0000, v97
	v_lshlrev_b32_e32 v106, 16, v98
	v_and_b32_e32 v98, 0xffff0000, v98
	v_lshlrev_b32_e32 v110, 16, v99
	v_and_b32_e32 v112, 0xffff0000, v99
	v_mul_f32_e32 v101, v100, v100
	v_mul_f32_e32 v97, v96, v96
	v_mul_f32_e32 v103, v102, v102
	v_mul_f32_e32 v105, v104, v104
	v_mul_f32_e32 v107, v106, v106
	v_mul_f32_e32 v99, v98, v98
	v_mul_f32_e32 v111, v110, v110
	v_mul_f32_e32 v113, v112, v112
	v_pk_add_f32 v[96:97], v[100:101], v[96:97]
	v_pk_add_f32 v[100:101], v[102:103], v[104:105]
	v_pk_add_f32 v[98:99], v[106:107], v[98:99]
	v_pk_add_f32 v[96:97], v[96:97], v[100:101]
	v_pk_add_f32 v[100:101], v[110:111], v[112:113]
	s_nop 0
	v_pk_add_f32 v[98:99], v[98:99], v[100:101]
	s_nop 0
	v_pk_add_f32 v[96:97], v[96:97], v[98:99]
	s_nop 0
	v_pk_add_f32 v[96:97], v[108:109], v[96:97]
	s_nop 0
	v_mov_b32_e32 v98, v96
	v_mov_b32_e32 v99, v97
	s_nop 0
	v_permlane16_swap_b32_e32 v96, v98
	v_permlane16_swap_b32_e32 v97, v99
	v_pk_add_f32 v[96:97], v[96:97], v[98:99]
	s_nop 0
	v_mov_b32_e32 v98, v96
	v_mov_b32_e32 v99, v97
	s_nop 0
	v_permlane32_swap_b32_e32 v96, v98
	v_permlane32_swap_b32_e32 v97, v99
	v_pk_add_f32 v[96:97], v[96:97], v[98:99]
	s_and_saveexec_b64 s[10:11], s[4:5]
	s_cbranch_execz .LBB0_234
	v_lshlrev_b64 v[100:101], 8, v[162:163]
	v_lshl_add_u64 v[100:101], s[16:17], 0, v[100:101]
	v_lshl_add_u64 v[100:101], s[50:51], 2, v[100:101]
	global_store_dwordx2 v[100:101], v[96:97], off

.LBB0_237:
	v_mov_b32_e32 v99, v98
	v_pk_mul_f32 v[84:85], v[84:85], v[98:99]
	v_mov_b32_e32 v88, v98
	v_and_b32_e32 v91, 0x7fffffff, v85
	v_and_b32_e32 v90, 0x7fffffff, v84
	v_pk_fma_f32 v[90:91], v[90:91], s[26:27], 1.0 op_sel_hi:[1,0,0]
	v_mov_b32_e32 v89, v98
	v_rcp_f32_e32 v90, v90
	v_rcp_f32_e32 v91, v91
	v_pk_mul_f32 v[86:87], v[86:87], v[88:89]
	v_pk_mul_f32 v[82:83], v[82:83], v[88:89]
	v_pk_mul_f32 v[80:81], v[80:81], v[98:99]
	v_mov_b64_e32 v[88:89], s[30:31]
	v_pk_mul_f32 v[98:99], v[84:85], v[84:85]
	v_pk_fma_f32 v[94:95], v[90:91], s[28:29], v[88:89] op_sel_hi:[1,0,0]
	v_pk_mul_f32 v[98:99], v[98:99], s[40:41] op_sel_hi:[1,0]
	v_pk_fma_f32 v[94:95], v[90:91], v[94:95], s[34:35] op_sel_hi:[1,1,0]
	v_exp_f32_e32 v98, v98
	v_exp_f32_e32 v99, v99
	v_pk_fma_f32 v[94:95], v[90:91], v[94:95], s[36:37] op_sel_hi:[1,1,0]
	v_and_b32_e32 v101, 0x7fffffff, v87
	v_and_b32_e32 v100, 0x7fffffff, v86
	v_pk_fma_f32 v[94:95], v[90:91], v[94:95], s[38:39] op_sel_hi:[1,1,0]
	v_pk_fma_f32 v[100:101], v[100:101], s[26:27], 1.0 op_sel_hi:[1,0,0]
	v_pk_mul_f32 v[90:91], v[90:91], v[94:95]
	v_rcp_f32_e32 v100, v100
	v_rcp_f32_e32 v101, v101
	v_pk_mul_f32 v[90:91], v[98:99], v[90:91]
	v_cmp_gt_f32_e32 vcc, 0, v84
	v_pk_mul_f32 v[98:99], v[84:85], v[90:91]
	v_pk_fma_f32 v[90:91], v[84:85], v[90:91], v[84:85] neg_lo:[1,0,0] neg_hi:[1,0,0]
	v_pk_mul_f32 v[94:95], v[86:87], v[86:87]
	v_cndmask_b32_e32 v98, v90, v98, vcc
	v_cmp_gt_f32_e32 vcc, 0, v85
	v_pk_fma_f32 v[84:85], v[100:101], s[28:29], v[88:89] op_sel_hi:[1,0,0]
	s_nop 0
	v_cndmask_b32_e32 v99, v91, v99, vcc
	v_pk_mul_f32 v[90:91], v[94:95], s[40:41] op_sel_hi:[1,0]
	v_pk_fma_f32 v[84:85], v[100:101], v[84:85], s[34:35] op_sel_hi:[1,1,0]
	v_exp_f32_e32 v90, v90
	v_exp_f32_e32 v91, v91
	v_pk_fma_f32 v[84:85], v[100:101], v[84:85], s[36:37] op_sel_hi:[1,1,0]
	v_and_b32_e32 v95, 0x7fffffff, v81
	v_and_b32_e32 v94, 0x7fffffff, v80
	v_pk_fma_f32 v[84:85], v[100:101], v[84:85], s[38:39] op_sel_hi:[1,1,0]
	v_pk_fma_f32 v[94:95], v[94:95], s[26:27], 1.0 op_sel_hi:[1,0,0]
	v_pk_mul_f32 v[84:85], v[100:101], v[84:85]
	v_rcp_f32_e32 v94, v94
	v_rcp_f32_e32 v95, v95
	v_pk_mul_f32 v[84:85], v[90:91], v[84:85]
	v_cmp_gt_f32_e32 vcc, 0, v86
	v_pk_mul_f32 v[90:91], v[86:87], v[84:85]
	v_pk_fma_f32 v[84:85], v[86:87], v[84:85], v[86:87] neg_lo:[1,0,0] neg_hi:[1,0,0]
	s_nop 0
	v_cndmask_b32_e32 v100, v84, v90, vcc
	v_cmp_gt_f32_e32 vcc, 0, v87
	v_pk_mul_f32 v[86:87], v[80:81], v[80:81]
	s_nop 0
	v_cndmask_b32_e32 v101, v85, v91, vcc
	v_pk_fma_f32 v[84:85], v[94:95], s[28:29], v[88:89] op_sel_hi:[1,0,0]
	v_pk_mul_f32 v[86:87], v[86:87], s[40:41] op_sel_hi:[1,0]
	v_pk_fma_f32 v[84:85], v[94:95], v[84:85], s[34:35] op_sel_hi:[1,1,0]
	v_exp_f32_e32 v86, v86
	v_pk_fma_f32 v[84:85], v[94:95], v[84:85], s[36:37] op_sel_hi:[1,1,0]
	v_exp_f32_e32 v87, v87
	v_pk_fma_f32 v[84:85], v[94:95], v[84:85], s[38:39] op_sel_hi:[1,1,0]
	v_cmp_gt_f32_e32 vcc, 0, v80
	v_pk_mul_f32 v[84:85], v[94:95], v[84:85]
	v_and_b32_e32 v95, 0x7fffffff, v83
	v_and_b32_e32 v94, 0x7fffffff, v82
	v_pk_fma_f32 v[94:95], v[94:95], s[26:27], 1.0 op_sel_hi:[1,0,0]
	v_pk_mul_f32 v[84:85], v[86:87], v[84:85]
	v_rcp_f32_e32 v94, v94
	v_rcp_f32_e32 v95, v95
	v_pk_mul_f32 v[86:87], v[80:81], v[84:85]
	v_pk_fma_f32 v[84:85], v[80:81], v[84:85], v[80:81] neg_lo:[1,0,0] neg_hi:[1,0,0]
	v_pk_mul_f32 v[90:91], v[82:83], v[82:83]
	v_cndmask_b32_e32 v86, v84, v86, vcc
	v_cmp_gt_f32_e32 vcc, 0, v81
	v_pk_fma_f32 v[80:81], v[94:95], s[28:29], v[88:89] op_sel_hi:[1,0,0]
	s_nop 0
	v_cndmask_b32_e32 v87, v85, v87, vcc
	v_pk_mul_f32 v[84:85], v[90:91], s[40:41] op_sel_hi:[1,0]
	v_pk_fma_f32 v[80:81], v[94:95], v[80:81], s[34:35] op_sel_hi:[1,1,0]
	v_exp_f32_e32 v84, v84
	v_exp_f32_e32 v85, v85
	v_pk_fma_f32 v[80:81], v[94:95], v[80:81], s[36:37] op_sel_hi:[1,1,0]
	v_cmp_gt_f32_e32 vcc, 0, v82
	v_pk_fma_f32 v[80:81], v[94:95], v[80:81], s[38:39] op_sel_hi:[1,1,0]
	s_nop 0
	v_pk_mul_f32 v[80:81], v[94:95], v[80:81]
	s_nop 0
	v_pk_mul_f32 v[80:81], v[84:85], v[80:81]
	s_nop 0
	v_pk_mul_f32 v[84:85], v[82:83], v[80:81]
	v_pk_fma_f32 v[80:81], v[82:83], v[80:81], v[82:83] neg_lo:[1,0,0] neg_hi:[1,0,0]
	s_nop 0
	v_cndmask_b32_e32 v84, v80, v84, vcc
	v_cmp_gt_f32_e32 vcc, 0, v83
	v_cvt_pk_bf16_f32 v80, v98, v99
	s_nop 1
	v_cndmask_b32_e32 v83, v81, v85, vcc
	s_and_b64 vcc, exec, s[8:9]
	v_cvt_pk_bf16_f32 v81, v100, v101
	v_cvt_pk_bf16_f32 v82, v86, v87
	v_cvt_pk_bf16_f32 v83, v84, v83
	global_store_dwordx4 v[96:97], v[80:83], off offset:256
	s_cbranch_vccnz .LBB0_241
	v_lshlrev_b32_e32 v84, 16, v80
	v_and_b32_e32 v80, 0xffff0000, v80
	v_lshlrev_b32_e32 v86, 16, v81
	v_and_b32_e32 v88, 0xffff0000, v81
	v_lshlrev_b32_e32 v90, 16, v82
	v_and_b32_e32 v82, 0xffff0000, v82
	v_lshlrev_b32_e32 v94, 16, v83
	v_and_b32_e32 v96, 0xffff0000, v83
	v_mul_f32_e32 v85, v84, v84
	v_mul_f32_e32 v81, v80, v80
	v_mul_f32_e32 v87, v86, v86
	v_mul_f32_e32 v89, v88, v88
	v_mul_f32_e32 v91, v90, v90
	v_mul_f32_e32 v83, v82, v82
	v_mul_f32_e32 v95, v94, v94
	v_mul_f32_e32 v97, v96, v96
	v_pk_add_f32 v[80:81], v[84:85], v[80:81]
	v_pk_add_f32 v[84:85], v[86:87], v[88:89]
	v_pk_add_f32 v[82:83], v[90:91], v[82:83]
	v_pk_add_f32 v[80:81], v[80:81], v[84:85]
	v_pk_add_f32 v[84:85], v[94:95], v[96:97]
	s_nop 0
	v_pk_add_f32 v[82:83], v[82:83], v[84:85]
	s_nop 0
	v_pk_add_f32 v[80:81], v[80:81], v[82:83]
	s_nop 0
	v_pk_add_f32 v[80:81], v[92:93], v[80:81]
	s_nop 0
	v_mov_b32_e32 v82, v80
	v_mov_b32_e32 v83, v81
	s_nop 0
	v_permlane16_swap_b32_e32 v80, v82
	v_permlane16_swap_b32_e32 v81, v83
	v_pk_add_f32 v[80:81], v[80:81], v[82:83]
	s_nop 0
	v_mov_b32_e32 v82, v80
	v_mov_b32_e32 v83, v81
	s_nop 0
	v_permlane32_swap_b32_e32 v80, v82
	v_permlane32_swap_b32_e32 v81, v83
	v_pk_add_f32 v[80:81], v[80:81], v[82:83]
	s_and_saveexec_b64 s[10:11], s[4:5]
	s_cbranch_execz .LBB0_240
	v_lshlrev_b64 v[84:85], 8, v[160:161]
	v_lshl_add_u64 v[84:85], s[16:17], 0, v[84:85]
	v_lshl_add_u64 v[84:85], s[50:51], 2, v[84:85]
	global_store_dwordx2 v[84:85], v[80:81], off

.LBB0_243:
	v_mov_b32_e32 v83, v82
	v_pk_mul_f32 v[68:69], v[68:69], v[82:83]
	v_mov_b32_e32 v72, v82
	v_and_b32_e32 v75, 0x7fffffff, v69
	v_and_b32_e32 v74, 0x7fffffff, v68
	v_pk_fma_f32 v[74:75], v[74:75], s[26:27], 1.0 op_sel_hi:[1,0,0]
	v_mov_b32_e32 v73, v82
	v_rcp_f32_e32 v74, v74
	v_rcp_f32_e32 v75, v75
	v_pk_mul_f32 v[70:71], v[70:71], v[72:73]
	v_pk_mul_f32 v[66:67], v[66:67], v[72:73]
	v_pk_mul_f32 v[64:65], v[64:65], v[82:83]
	v_mov_b64_e32 v[72:73], s[30:31]
	v_pk_mul_f32 v[82:83], v[68:69], v[68:69]
	v_pk_fma_f32 v[78:79], v[74:75], s[28:29], v[72:73] op_sel_hi:[1,0,0]
	v_pk_mul_f32 v[82:83], v[82:83], s[40:41] op_sel_hi:[1,0]
	v_pk_fma_f32 v[78:79], v[74:75], v[78:79], s[34:35] op_sel_hi:[1,1,0]
	v_exp_f32_e32 v82, v82
	v_exp_f32_e32 v83, v83
	v_pk_fma_f32 v[78:79], v[74:75], v[78:79], s[36:37] op_sel_hi:[1,1,0]
	v_and_b32_e32 v85, 0x7fffffff, v71
	v_and_b32_e32 v84, 0x7fffffff, v70
	v_pk_fma_f32 v[78:79], v[74:75], v[78:79], s[38:39] op_sel_hi:[1,1,0]
	v_pk_fma_f32 v[84:85], v[84:85], s[26:27], 1.0 op_sel_hi:[1,0,0]
	v_pk_mul_f32 v[74:75], v[74:75], v[78:79]
	v_rcp_f32_e32 v84, v84
	v_rcp_f32_e32 v85, v85
	v_pk_mul_f32 v[74:75], v[82:83], v[74:75]
	v_cmp_gt_f32_e32 vcc, 0, v68
	v_pk_mul_f32 v[82:83], v[68:69], v[74:75]
	v_pk_fma_f32 v[74:75], v[68:69], v[74:75], v[68:69] neg_lo:[1,0,0] neg_hi:[1,0,0]
	v_pk_mul_f32 v[78:79], v[70:71], v[70:71]
	v_cndmask_b32_e32 v82, v74, v82, vcc
	v_cmp_gt_f32_e32 vcc, 0, v69
	v_pk_fma_f32 v[68:69], v[84:85], s[28:29], v[72:73] op_sel_hi:[1,0,0]
	s_nop 0
	v_cndmask_b32_e32 v83, v75, v83, vcc
	v_pk_mul_f32 v[74:75], v[78:79], s[40:41] op_sel_hi:[1,0]
	v_pk_fma_f32 v[68:69], v[84:85], v[68:69], s[34:35] op_sel_hi:[1,1,0]
	v_exp_f32_e32 v74, v74
	v_exp_f32_e32 v75, v75
	v_pk_fma_f32 v[68:69], v[84:85], v[68:69], s[36:37] op_sel_hi:[1,1,0]
	v_and_b32_e32 v79, 0x7fffffff, v65
	v_and_b32_e32 v78, 0x7fffffff, v64
	v_pk_fma_f32 v[68:69], v[84:85], v[68:69], s[38:39] op_sel_hi:[1,1,0]
	v_pk_fma_f32 v[78:79], v[78:79], s[26:27], 1.0 op_sel_hi:[1,0,0]
	v_pk_mul_f32 v[68:69], v[84:85], v[68:69]
	v_rcp_f32_e32 v78, v78
	v_rcp_f32_e32 v79, v79
	v_pk_mul_f32 v[68:69], v[74:75], v[68:69]
	v_cmp_gt_f32_e32 vcc, 0, v70
	v_pk_mul_f32 v[74:75], v[70:71], v[68:69]
	v_pk_fma_f32 v[68:69], v[70:71], v[68:69], v[70:71] neg_lo:[1,0,0] neg_hi:[1,0,0]
	s_nop 0
	v_cndmask_b32_e32 v84, v68, v74, vcc
	v_cmp_gt_f32_e32 vcc, 0, v71
	v_pk_mul_f32 v[70:71], v[64:65], v[64:65]
	s_nop 0
	v_cndmask_b32_e32 v85, v69, v75, vcc
	v_pk_fma_f32 v[68:69], v[78:79], s[28:29], v[72:73] op_sel_hi:[1,0,0]
	v_pk_mul_f32 v[70:71], v[70:71], s[40:41] op_sel_hi:[1,0]
	v_pk_fma_f32 v[68:69], v[78:79], v[68:69], s[34:35] op_sel_hi:[1,1,0]
	v_exp_f32_e32 v70, v70
	v_pk_fma_f32 v[68:69], v[78:79], v[68:69], s[36:37] op_sel_hi:[1,1,0]
	v_exp_f32_e32 v71, v71
	v_pk_fma_f32 v[68:69], v[78:79], v[68:69], s[38:39] op_sel_hi:[1,1,0]
	v_cmp_gt_f32_e32 vcc, 0, v64
	v_pk_mul_f32 v[68:69], v[78:79], v[68:69]
	v_and_b32_e32 v79, 0x7fffffff, v67
	v_and_b32_e32 v78, 0x7fffffff, v66
	v_pk_fma_f32 v[78:79], v[78:79], s[26:27], 1.0 op_sel_hi:[1,0,0]
	v_pk_mul_f32 v[68:69], v[70:71], v[68:69]
	v_rcp_f32_e32 v78, v78
	v_rcp_f32_e32 v79, v79
	v_pk_mul_f32 v[70:71], v[64:65], v[68:69]
	v_pk_fma_f32 v[68:69], v[64:65], v[68:69], v[64:65] neg_lo:[1,0,0] neg_hi:[1,0,0]
	v_pk_mul_f32 v[74:75], v[66:67], v[66:67]
	v_cndmask_b32_e32 v70, v68, v70, vcc
	v_cmp_gt_f32_e32 vcc, 0, v65
	v_pk_fma_f32 v[64:65], v[78:79], s[28:29], v[72:73] op_sel_hi:[1,0,0]
	s_nop 0
	v_cndmask_b32_e32 v71, v69, v71, vcc
	v_pk_mul_f32 v[68:69], v[74:75], s[40:41] op_sel_hi:[1,0]
	v_pk_fma_f32 v[64:65], v[78:79], v[64:65], s[34:35] op_sel_hi:[1,1,0]
	v_exp_f32_e32 v68, v68
	v_exp_f32_e32 v69, v69
	v_pk_fma_f32 v[64:65], v[78:79], v[64:65], s[36:37] op_sel_hi:[1,1,0]
	v_cmp_gt_f32_e32 vcc, 0, v66
	v_pk_fma_f32 v[64:65], v[78:79], v[64:65], s[38:39] op_sel_hi:[1,1,0]
	s_nop 0
	v_pk_mul_f32 v[64:65], v[78:79], v[64:65]
	s_nop 0
	v_pk_mul_f32 v[64:65], v[68:69], v[64:65]
	s_nop 0
	v_pk_mul_f32 v[68:69], v[66:67], v[64:65]
	v_pk_fma_f32 v[64:65], v[66:67], v[64:65], v[66:67] neg_lo:[1,0,0] neg_hi:[1,0,0]
	s_nop 0
	v_cndmask_b32_e32 v68, v64, v68, vcc
	v_cmp_gt_f32_e32 vcc, 0, v67
	v_cvt_pk_bf16_f32 v64, v82, v83
	s_nop 1
	v_cndmask_b32_e32 v67, v65, v69, vcc
	s_and_b64 vcc, exec, s[8:9]
	v_cvt_pk_bf16_f32 v65, v84, v85
	v_cvt_pk_bf16_f32 v66, v70, v71
	v_cvt_pk_bf16_f32 v67, v68, v67
	global_store_dwordx4 v[80:81], v[64:67], off offset:256
	s_cbranch_vccnz .LBB0_247
	v_lshlrev_b32_e32 v68, 16, v64
	v_and_b32_e32 v64, 0xffff0000, v64
	v_lshlrev_b32_e32 v70, 16, v65
	v_and_b32_e32 v72, 0xffff0000, v65
	v_lshlrev_b32_e32 v74, 16, v66
	v_and_b32_e32 v66, 0xffff0000, v66
	v_lshlrev_b32_e32 v78, 16, v67
	v_and_b32_e32 v80, 0xffff0000, v67
	v_mul_f32_e32 v69, v68, v68
	v_mul_f32_e32 v65, v64, v64
	v_mul_f32_e32 v71, v70, v70
	v_mul_f32_e32 v73, v72, v72
	v_mul_f32_e32 v75, v74, v74
	v_mul_f32_e32 v67, v66, v66
	v_mul_f32_e32 v79, v78, v78
	v_mul_f32_e32 v81, v80, v80
	v_pk_add_f32 v[64:65], v[68:69], v[64:65]
	v_pk_add_f32 v[68:69], v[70:71], v[72:73]
	v_pk_add_f32 v[66:67], v[74:75], v[66:67]
	v_pk_add_f32 v[64:65], v[64:65], v[68:69]
	v_pk_add_f32 v[68:69], v[78:79], v[80:81]
	s_nop 0
	v_pk_add_f32 v[66:67], v[66:67], v[68:69]
	s_nop 0
	v_pk_add_f32 v[64:65], v[64:65], v[66:67]
	s_nop 0
	v_pk_add_f32 v[64:65], v[76:77], v[64:65]
	s_nop 0
	v_mov_b32_e32 v66, v64
	v_mov_b32_e32 v67, v65
	s_nop 0
	v_permlane16_swap_b32_e32 v64, v66
	v_permlane16_swap_b32_e32 v65, v67
	v_pk_add_f32 v[64:65], v[64:65], v[66:67]
	s_nop 0
	v_mov_b32_e32 v66, v64
	v_mov_b32_e32 v67, v65
	s_nop 0
	v_permlane32_swap_b32_e32 v64, v66
	v_permlane32_swap_b32_e32 v65, v67
	v_pk_add_f32 v[64:65], v[64:65], v[66:67]
	s_and_saveexec_b64 s[10:11], s[4:5]
	s_cbranch_execz .LBB0_246
	v_lshlrev_b64 v[68:69], 8, v[158:159]
	v_lshl_add_u64 v[68:69], s[16:17], 0, v[68:69]
	v_lshl_add_u64 v[68:69], s[50:51], 2, v[68:69]
	global_store_dwordx2 v[68:69], v[64:65], off

.LBB0_249:
	v_mov_b32_e32 v67, v66
	v_pk_mul_f32 v[52:53], v[52:53], v[66:67]
	v_mov_b32_e32 v56, v66
	v_and_b32_e32 v59, 0x7fffffff, v53
	v_and_b32_e32 v58, 0x7fffffff, v52
	v_pk_fma_f32 v[58:59], v[58:59], s[26:27], 1.0 op_sel_hi:[1,0,0]
	v_mov_b32_e32 v57, v66
	v_rcp_f32_e32 v58, v58
	v_rcp_f32_e32 v59, v59
	v_pk_mul_f32 v[54:55], v[54:55], v[56:57]
	v_pk_mul_f32 v[50:51], v[50:51], v[56:57]
	v_pk_mul_f32 v[48:49], v[48:49], v[66:67]
	v_mov_b64_e32 v[56:57], s[30:31]
	v_pk_mul_f32 v[66:67], v[52:53], v[52:53]
	v_pk_fma_f32 v[62:63], v[58:59], s[28:29], v[56:57] op_sel_hi:[1,0,0]
	v_pk_mul_f32 v[66:67], v[66:67], s[40:41] op_sel_hi:[1,0]
	v_pk_fma_f32 v[62:63], v[58:59], v[62:63], s[34:35] op_sel_hi:[1,1,0]
	v_exp_f32_e32 v66, v66
	v_exp_f32_e32 v67, v67
	v_pk_fma_f32 v[62:63], v[58:59], v[62:63], s[36:37] op_sel_hi:[1,1,0]
	v_and_b32_e32 v69, 0x7fffffff, v55
	v_and_b32_e32 v68, 0x7fffffff, v54
	v_pk_fma_f32 v[62:63], v[58:59], v[62:63], s[38:39] op_sel_hi:[1,1,0]
	v_pk_fma_f32 v[68:69], v[68:69], s[26:27], 1.0 op_sel_hi:[1,0,0]
	v_pk_mul_f32 v[58:59], v[58:59], v[62:63]
	v_rcp_f32_e32 v68, v68
	v_rcp_f32_e32 v69, v69
	v_pk_mul_f32 v[58:59], v[66:67], v[58:59]
	v_cmp_gt_f32_e32 vcc, 0, v52
	v_pk_mul_f32 v[66:67], v[52:53], v[58:59]
	v_pk_fma_f32 v[58:59], v[52:53], v[58:59], v[52:53] neg_lo:[1,0,0] neg_hi:[1,0,0]
	v_pk_mul_f32 v[62:63], v[54:55], v[54:55]
	v_cndmask_b32_e32 v66, v58, v66, vcc
	v_cmp_gt_f32_e32 vcc, 0, v53
	v_pk_fma_f32 v[52:53], v[68:69], s[28:29], v[56:57] op_sel_hi:[1,0,0]
	s_nop 0
	v_cndmask_b32_e32 v67, v59, v67, vcc
	v_pk_mul_f32 v[58:59], v[62:63], s[40:41] op_sel_hi:[1,0]
	v_pk_fma_f32 v[52:53], v[68:69], v[52:53], s[34:35] op_sel_hi:[1,1,0]
	v_exp_f32_e32 v58, v58
	v_exp_f32_e32 v59, v59
	v_pk_fma_f32 v[52:53], v[68:69], v[52:53], s[36:37] op_sel_hi:[1,1,0]
	v_and_b32_e32 v63, 0x7fffffff, v49
	v_and_b32_e32 v62, 0x7fffffff, v48
	v_pk_fma_f32 v[52:53], v[68:69], v[52:53], s[38:39] op_sel_hi:[1,1,0]
	v_pk_fma_f32 v[62:63], v[62:63], s[26:27], 1.0 op_sel_hi:[1,0,0]
	v_pk_mul_f32 v[52:53], v[68:69], v[52:53]
	v_rcp_f32_e32 v62, v62
	v_rcp_f32_e32 v63, v63
	v_pk_mul_f32 v[52:53], v[58:59], v[52:53]
	v_cmp_gt_f32_e32 vcc, 0, v54
	v_pk_mul_f32 v[58:59], v[54:55], v[52:53]
	v_pk_fma_f32 v[52:53], v[54:55], v[52:53], v[54:55] neg_lo:[1,0,0] neg_hi:[1,0,0]
	s_nop 0
	v_cndmask_b32_e32 v68, v52, v58, vcc
	v_cmp_gt_f32_e32 vcc, 0, v55
	v_pk_mul_f32 v[54:55], v[48:49], v[48:49]
	s_nop 0
	v_cndmask_b32_e32 v69, v53, v59, vcc
	v_pk_fma_f32 v[52:53], v[62:63], s[28:29], v[56:57] op_sel_hi:[1,0,0]
	v_pk_mul_f32 v[54:55], v[54:55], s[40:41] op_sel_hi:[1,0]
	v_pk_fma_f32 v[52:53], v[62:63], v[52:53], s[34:35] op_sel_hi:[1,1,0]
	v_exp_f32_e32 v54, v54
	v_pk_fma_f32 v[52:53], v[62:63], v[52:53], s[36:37] op_sel_hi:[1,1,0]
	v_exp_f32_e32 v55, v55
	v_pk_fma_f32 v[52:53], v[62:63], v[52:53], s[38:39] op_sel_hi:[1,1,0]
	v_cmp_gt_f32_e32 vcc, 0, v48
	v_pk_mul_f32 v[52:53], v[62:63], v[52:53]
	v_and_b32_e32 v63, 0x7fffffff, v51
	v_and_b32_e32 v62, 0x7fffffff, v50
	v_pk_fma_f32 v[62:63], v[62:63], s[26:27], 1.0 op_sel_hi:[1,0,0]
	v_pk_mul_f32 v[52:53], v[54:55], v[52:53]
	v_rcp_f32_e32 v62, v62
	v_rcp_f32_e32 v63, v63
	v_pk_mul_f32 v[54:55], v[48:49], v[52:53]
	v_pk_fma_f32 v[52:53], v[48:49], v[52:53], v[48:49] neg_lo:[1,0,0] neg_hi:[1,0,0]
	v_pk_mul_f32 v[58:59], v[50:51], v[50:51]
	v_cndmask_b32_e32 v54, v52, v54, vcc
	v_cmp_gt_f32_e32 vcc, 0, v49
	v_pk_fma_f32 v[48:49], v[62:63], s[28:29], v[56:57] op_sel_hi:[1,0,0]
	s_nop 0
	v_cndmask_b32_e32 v55, v53, v55, vcc
	v_pk_mul_f32 v[52:53], v[58:59], s[40:41] op_sel_hi:[1,0]
	v_pk_fma_f32 v[48:49], v[62:63], v[48:49], s[34:35] op_sel_hi:[1,1,0]
	v_exp_f32_e32 v52, v52
	v_exp_f32_e32 v53, v53
	v_pk_fma_f32 v[48:49], v[62:63], v[48:49], s[36:37] op_sel_hi:[1,1,0]
	v_cmp_gt_f32_e32 vcc, 0, v50
	v_pk_fma_f32 v[48:49], v[62:63], v[48:49], s[38:39] op_sel_hi:[1,1,0]
	s_nop 0
	v_pk_mul_f32 v[48:49], v[62:63], v[48:49]
	s_nop 0
	v_pk_mul_f32 v[48:49], v[52:53], v[48:49]
	s_nop 0
	v_pk_mul_f32 v[52:53], v[50:51], v[48:49]
	v_pk_fma_f32 v[48:49], v[50:51], v[48:49], v[50:51] neg_lo:[1,0,0] neg_hi:[1,0,0]
	s_nop 0
	v_cndmask_b32_e32 v52, v48, v52, vcc
	v_cmp_gt_f32_e32 vcc, 0, v51
	v_cvt_pk_bf16_f32 v48, v66, v67
	s_nop 1
	v_cndmask_b32_e32 v51, v49, v53, vcc
	s_and_b64 vcc, exec, s[8:9]
	v_cvt_pk_bf16_f32 v49, v68, v69
	v_cvt_pk_bf16_f32 v50, v54, v55
	v_cvt_pk_bf16_f32 v51, v52, v51
	global_store_dwordx4 v[64:65], v[48:51], off offset:256
	s_cbranch_vccnz .LBB0_253
	v_lshlrev_b32_e32 v52, 16, v48
	v_and_b32_e32 v48, 0xffff0000, v48
	v_lshlrev_b32_e32 v54, 16, v49
	v_and_b32_e32 v56, 0xffff0000, v49
	v_lshlrev_b32_e32 v58, 16, v50
	v_and_b32_e32 v50, 0xffff0000, v50
	v_lshlrev_b32_e32 v62, 16, v51
	v_and_b32_e32 v64, 0xffff0000, v51
	v_mul_f32_e32 v53, v52, v52
	v_mul_f32_e32 v49, v48, v48
	v_mul_f32_e32 v55, v54, v54
	v_mul_f32_e32 v57, v56, v56
	v_mul_f32_e32 v59, v58, v58
	v_mul_f32_e32 v51, v50, v50
	v_mul_f32_e32 v63, v62, v62
	v_mul_f32_e32 v65, v64, v64
	v_pk_add_f32 v[48:49], v[52:53], v[48:49]
	v_pk_add_f32 v[52:53], v[54:55], v[56:57]
	v_pk_add_f32 v[50:51], v[58:59], v[50:51]
	v_pk_add_f32 v[48:49], v[48:49], v[52:53]
	v_pk_add_f32 v[52:53], v[62:63], v[64:65]
	s_nop 0
	v_pk_add_f32 v[50:51], v[50:51], v[52:53]
	s_nop 0
	v_pk_add_f32 v[48:49], v[48:49], v[50:51]
	s_nop 0
	v_pk_add_f32 v[48:49], v[60:61], v[48:49]
	s_nop 0
	v_mov_b32_e32 v50, v48
	v_mov_b32_e32 v51, v49
	s_nop 0
	v_permlane16_swap_b32_e32 v48, v50
	v_permlane16_swap_b32_e32 v49, v51
	v_pk_add_f32 v[48:49], v[48:49], v[50:51]
	s_nop 0
	v_mov_b32_e32 v50, v48
	v_mov_b32_e32 v51, v49
	s_nop 0
	v_permlane32_swap_b32_e32 v48, v50
	v_permlane32_swap_b32_e32 v49, v51
	v_pk_add_f32 v[48:49], v[48:49], v[50:51]
	s_and_saveexec_b64 s[10:11], s[4:5]
	s_cbranch_execz .LBB0_252
	v_lshlrev_b64 v[52:53], 8, v[156:157]
	v_lshl_add_u64 v[52:53], s[16:17], 0, v[52:53]
	v_lshl_add_u64 v[52:53], s[50:51], 2, v[52:53]
	global_store_dwordx2 v[52:53], v[48:49], off

.LBB0_255:
	v_mov_b32_e32 v51, v50
	v_pk_mul_f32 v[36:37], v[36:37], v[50:51]
	v_mov_b32_e32 v40, v50
	v_and_b32_e32 v43, 0x7fffffff, v37
	v_and_b32_e32 v42, 0x7fffffff, v36
	v_pk_fma_f32 v[42:43], v[42:43], s[26:27], 1.0 op_sel_hi:[1,0,0]
	v_mov_b32_e32 v41, v50
	v_rcp_f32_e32 v42, v42
	v_rcp_f32_e32 v43, v43
	v_pk_mul_f32 v[38:39], v[38:39], v[40:41]
	v_pk_mul_f32 v[34:35], v[34:35], v[40:41]
	v_pk_mul_f32 v[32:33], v[32:33], v[50:51]
	v_mov_b64_e32 v[40:41], s[30:31]
	v_pk_mul_f32 v[50:51], v[36:37], v[36:37]
	v_pk_fma_f32 v[46:47], v[42:43], s[28:29], v[40:41] op_sel_hi:[1,0,0]
	v_pk_mul_f32 v[50:51], v[50:51], s[40:41] op_sel_hi:[1,0]
	v_pk_fma_f32 v[46:47], v[42:43], v[46:47], s[34:35] op_sel_hi:[1,1,0]
	v_exp_f32_e32 v50, v50
	v_exp_f32_e32 v51, v51
	v_pk_fma_f32 v[46:47], v[42:43], v[46:47], s[36:37] op_sel_hi:[1,1,0]
	v_and_b32_e32 v53, 0x7fffffff, v39
	v_and_b32_e32 v52, 0x7fffffff, v38
	v_pk_fma_f32 v[46:47], v[42:43], v[46:47], s[38:39] op_sel_hi:[1,1,0]
	v_pk_fma_f32 v[52:53], v[52:53], s[26:27], 1.0 op_sel_hi:[1,0,0]
	v_pk_mul_f32 v[42:43], v[42:43], v[46:47]
	v_rcp_f32_e32 v52, v52
	v_rcp_f32_e32 v53, v53
	v_pk_mul_f32 v[42:43], v[50:51], v[42:43]
	v_cmp_gt_f32_e32 vcc, 0, v36
	v_pk_mul_f32 v[50:51], v[36:37], v[42:43]
	v_pk_fma_f32 v[42:43], v[36:37], v[42:43], v[36:37] neg_lo:[1,0,0] neg_hi:[1,0,0]
	v_pk_mul_f32 v[46:47], v[38:39], v[38:39]
	v_cndmask_b32_e32 v50, v42, v50, vcc
	v_cmp_gt_f32_e32 vcc, 0, v37
	v_pk_fma_f32 v[36:37], v[52:53], s[28:29], v[40:41] op_sel_hi:[1,0,0]
	s_nop 0
	v_cndmask_b32_e32 v51, v43, v51, vcc
	v_pk_mul_f32 v[42:43], v[46:47], s[40:41] op_sel_hi:[1,0]
	v_pk_fma_f32 v[36:37], v[52:53], v[36:37], s[34:35] op_sel_hi:[1,1,0]
	v_exp_f32_e32 v42, v42
	v_exp_f32_e32 v43, v43
	v_pk_fma_f32 v[36:37], v[52:53], v[36:37], s[36:37] op_sel_hi:[1,1,0]
	v_and_b32_e32 v47, 0x7fffffff, v33
	v_and_b32_e32 v46, 0x7fffffff, v32
	v_pk_fma_f32 v[36:37], v[52:53], v[36:37], s[38:39] op_sel_hi:[1,1,0]
	v_pk_fma_f32 v[46:47], v[46:47], s[26:27], 1.0 op_sel_hi:[1,0,0]
	v_pk_mul_f32 v[36:37], v[52:53], v[36:37]
	v_rcp_f32_e32 v46, v46
	v_rcp_f32_e32 v47, v47
	v_pk_mul_f32 v[36:37], v[42:43], v[36:37]
	v_cmp_gt_f32_e32 vcc, 0, v38
	v_pk_mul_f32 v[42:43], v[38:39], v[36:37]
	v_pk_fma_f32 v[36:37], v[38:39], v[36:37], v[38:39] neg_lo:[1,0,0] neg_hi:[1,0,0]
	s_nop 0
	v_cndmask_b32_e32 v52, v36, v42, vcc
	v_cmp_gt_f32_e32 vcc, 0, v39
	v_pk_mul_f32 v[38:39], v[32:33], v[32:33]
	s_nop 0
	v_cndmask_b32_e32 v53, v37, v43, vcc
	v_pk_fma_f32 v[36:37], v[46:47], s[28:29], v[40:41] op_sel_hi:[1,0,0]
	v_pk_mul_f32 v[38:39], v[38:39], s[40:41] op_sel_hi:[1,0]
	v_pk_fma_f32 v[36:37], v[46:47], v[36:37], s[34:35] op_sel_hi:[1,1,0]
	v_exp_f32_e32 v38, v38
	v_pk_fma_f32 v[36:37], v[46:47], v[36:37], s[36:37] op_sel_hi:[1,1,0]
	v_exp_f32_e32 v39, v39
	v_pk_fma_f32 v[36:37], v[46:47], v[36:37], s[38:39] op_sel_hi:[1,1,0]
	v_cmp_gt_f32_e32 vcc, 0, v32
	v_pk_mul_f32 v[36:37], v[46:47], v[36:37]
	v_and_b32_e32 v47, 0x7fffffff, v35
	v_and_b32_e32 v46, 0x7fffffff, v34
	v_pk_fma_f32 v[46:47], v[46:47], s[26:27], 1.0 op_sel_hi:[1,0,0]
	v_pk_mul_f32 v[36:37], v[38:39], v[36:37]
	v_rcp_f32_e32 v46, v46
	v_rcp_f32_e32 v47, v47
	v_pk_mul_f32 v[38:39], v[32:33], v[36:37]
	v_pk_fma_f32 v[36:37], v[32:33], v[36:37], v[32:33] neg_lo:[1,0,0] neg_hi:[1,0,0]
	v_pk_mul_f32 v[42:43], v[34:35], v[34:35]
	v_cndmask_b32_e32 v38, v36, v38, vcc
	v_cmp_gt_f32_e32 vcc, 0, v33
	v_pk_fma_f32 v[32:33], v[46:47], s[28:29], v[40:41] op_sel_hi:[1,0,0]
	s_nop 0
	v_cndmask_b32_e32 v39, v37, v39, vcc
	v_pk_mul_f32 v[36:37], v[42:43], s[40:41] op_sel_hi:[1,0]
	v_pk_fma_f32 v[32:33], v[46:47], v[32:33], s[34:35] op_sel_hi:[1,1,0]
	v_exp_f32_e32 v36, v36
	v_exp_f32_e32 v37, v37
	v_pk_fma_f32 v[32:33], v[46:47], v[32:33], s[36:37] op_sel_hi:[1,1,0]
	v_cmp_gt_f32_e32 vcc, 0, v34
	v_pk_fma_f32 v[32:33], v[46:47], v[32:33], s[38:39] op_sel_hi:[1,1,0]
	s_nop 0
	v_pk_mul_f32 v[32:33], v[46:47], v[32:33]
	s_nop 0
	v_pk_mul_f32 v[32:33], v[36:37], v[32:33]
	s_nop 0
	v_pk_mul_f32 v[36:37], v[34:35], v[32:33]
	v_pk_fma_f32 v[32:33], v[34:35], v[32:33], v[34:35] neg_lo:[1,0,0] neg_hi:[1,0,0]
	s_nop 0
	v_cndmask_b32_e32 v36, v32, v36, vcc
	v_cmp_gt_f32_e32 vcc, 0, v35
	v_cvt_pk_bf16_f32 v32, v50, v51
	s_nop 1
	v_cndmask_b32_e32 v35, v33, v37, vcc
	s_and_b64 vcc, exec, s[8:9]
	v_cvt_pk_bf16_f32 v33, v52, v53
	v_cvt_pk_bf16_f32 v34, v38, v39
	v_cvt_pk_bf16_f32 v35, v36, v35
	global_store_dwordx4 v[48:49], v[32:35], off offset:256
	s_cbranch_vccnz .LBB0_259
	v_lshlrev_b32_e32 v36, 16, v32
	v_and_b32_e32 v32, 0xffff0000, v32
	v_lshlrev_b32_e32 v38, 16, v33
	v_and_b32_e32 v40, 0xffff0000, v33
	v_lshlrev_b32_e32 v42, 16, v34
	v_and_b32_e32 v34, 0xffff0000, v34
	v_lshlrev_b32_e32 v46, 16, v35
	v_and_b32_e32 v48, 0xffff0000, v35
	v_mul_f32_e32 v37, v36, v36
	v_mul_f32_e32 v33, v32, v32
	v_mul_f32_e32 v39, v38, v38
	v_mul_f32_e32 v41, v40, v40
	v_mul_f32_e32 v43, v42, v42
	v_mul_f32_e32 v35, v34, v34
	v_mul_f32_e32 v47, v46, v46
	v_mul_f32_e32 v49, v48, v48
	v_pk_add_f32 v[32:33], v[36:37], v[32:33]
	v_pk_add_f32 v[36:37], v[38:39], v[40:41]
	v_pk_add_f32 v[34:35], v[42:43], v[34:35]
	v_pk_add_f32 v[32:33], v[32:33], v[36:37]
	v_pk_add_f32 v[36:37], v[46:47], v[48:49]
	s_nop 0
	v_pk_add_f32 v[34:35], v[34:35], v[36:37]
	s_nop 0
	v_pk_add_f32 v[32:33], v[32:33], v[34:35]
	s_nop 0
	v_pk_add_f32 v[32:33], v[44:45], v[32:33]
	s_nop 0
	v_mov_b32_e32 v34, v32
	v_mov_b32_e32 v35, v33
	s_nop 0
	v_permlane16_swap_b32_e32 v32, v34
	v_permlane16_swap_b32_e32 v33, v35
	v_pk_add_f32 v[32:33], v[32:33], v[34:35]
	s_nop 0
	v_mov_b32_e32 v34, v32
	v_mov_b32_e32 v35, v33
	s_nop 0
	v_permlane32_swap_b32_e32 v32, v34
	v_permlane32_swap_b32_e32 v33, v35
	v_pk_add_f32 v[32:33], v[32:33], v[34:35]
	s_and_saveexec_b64 s[10:11], s[4:5]
	s_cbranch_execz .LBB0_258
	v_lshlrev_b64 v[36:37], 8, v[154:155]
	v_lshl_add_u64 v[36:37], s[16:17], 0, v[36:37]
	v_lshl_add_u64 v[36:37], s[50:51], 2, v[36:37]
	global_store_dwordx2 v[36:37], v[32:33], off

.LBB0_261:
	v_mov_b32_e32 v35, v34
	v_pk_mul_f32 v[20:21], v[20:21], v[34:35]
	v_mov_b32_e32 v24, v34
	v_and_b32_e32 v27, 0x7fffffff, v21
	v_and_b32_e32 v26, 0x7fffffff, v20
	v_pk_fma_f32 v[26:27], v[26:27], s[26:27], 1.0 op_sel_hi:[1,0,0]
	v_mov_b32_e32 v25, v34
	v_rcp_f32_e32 v26, v26
	v_rcp_f32_e32 v27, v27
	v_pk_mul_f32 v[22:23], v[22:23], v[24:25]
	v_pk_mul_f32 v[18:19], v[18:19], v[24:25]
	v_pk_mul_f32 v[16:17], v[16:17], v[34:35]
	v_mov_b64_e32 v[24:25], s[30:31]
	v_pk_mul_f32 v[34:35], v[20:21], v[20:21]
	v_pk_fma_f32 v[30:31], v[26:27], s[28:29], v[24:25] op_sel_hi:[1,0,0]
	v_pk_mul_f32 v[34:35], v[34:35], s[40:41] op_sel_hi:[1,0]
	v_pk_fma_f32 v[30:31], v[26:27], v[30:31], s[34:35] op_sel_hi:[1,1,0]
	v_exp_f32_e32 v34, v34
	v_exp_f32_e32 v35, v35
	v_pk_fma_f32 v[30:31], v[26:27], v[30:31], s[36:37] op_sel_hi:[1,1,0]
	v_and_b32_e32 v37, 0x7fffffff, v23
	v_and_b32_e32 v36, 0x7fffffff, v22
	v_pk_fma_f32 v[30:31], v[26:27], v[30:31], s[38:39] op_sel_hi:[1,1,0]
	v_pk_fma_f32 v[36:37], v[36:37], s[26:27], 1.0 op_sel_hi:[1,0,0]
	v_pk_mul_f32 v[26:27], v[26:27], v[30:31]
	v_rcp_f32_e32 v36, v36
	v_rcp_f32_e32 v37, v37
	v_pk_mul_f32 v[26:27], v[34:35], v[26:27]
	v_cmp_gt_f32_e32 vcc, 0, v20
	v_pk_mul_f32 v[34:35], v[20:21], v[26:27]
	v_pk_fma_f32 v[26:27], v[20:21], v[26:27], v[20:21] neg_lo:[1,0,0] neg_hi:[1,0,0]
	v_pk_mul_f32 v[30:31], v[22:23], v[22:23]
	v_cndmask_b32_e32 v34, v26, v34, vcc
	v_cmp_gt_f32_e32 vcc, 0, v21
	v_pk_fma_f32 v[20:21], v[36:37], s[28:29], v[24:25] op_sel_hi:[1,0,0]
	s_nop 0
	v_cndmask_b32_e32 v35, v27, v35, vcc
	v_pk_mul_f32 v[26:27], v[30:31], s[40:41] op_sel_hi:[1,0]
	v_pk_fma_f32 v[20:21], v[36:37], v[20:21], s[34:35] op_sel_hi:[1,1,0]
	v_exp_f32_e32 v26, v26
	v_exp_f32_e32 v27, v27
	v_pk_fma_f32 v[20:21], v[36:37], v[20:21], s[36:37] op_sel_hi:[1,1,0]
	v_and_b32_e32 v31, 0x7fffffff, v17
	v_and_b32_e32 v30, 0x7fffffff, v16
	v_pk_fma_f32 v[20:21], v[36:37], v[20:21], s[38:39] op_sel_hi:[1,1,0]
	v_pk_fma_f32 v[30:31], v[30:31], s[26:27], 1.0 op_sel_hi:[1,0,0]
	v_pk_mul_f32 v[20:21], v[36:37], v[20:21]
	v_rcp_f32_e32 v30, v30
	v_rcp_f32_e32 v31, v31
	v_pk_mul_f32 v[20:21], v[26:27], v[20:21]
	v_cmp_gt_f32_e32 vcc, 0, v22
	v_pk_mul_f32 v[26:27], v[22:23], v[20:21]
	v_pk_fma_f32 v[20:21], v[22:23], v[20:21], v[22:23] neg_lo:[1,0,0] neg_hi:[1,0,0]
	s_nop 0
	v_cndmask_b32_e32 v36, v20, v26, vcc
	v_cmp_gt_f32_e32 vcc, 0, v23
	v_pk_mul_f32 v[22:23], v[16:17], v[16:17]
	s_nop 0
	v_cndmask_b32_e32 v37, v21, v27, vcc
	v_pk_fma_f32 v[20:21], v[30:31], s[28:29], v[24:25] op_sel_hi:[1,0,0]
	v_pk_mul_f32 v[22:23], v[22:23], s[40:41] op_sel_hi:[1,0]
	v_pk_fma_f32 v[20:21], v[30:31], v[20:21], s[34:35] op_sel_hi:[1,1,0]
	v_exp_f32_e32 v22, v22
	v_pk_fma_f32 v[20:21], v[30:31], v[20:21], s[36:37] op_sel_hi:[1,1,0]
	v_exp_f32_e32 v23, v23
	v_pk_fma_f32 v[20:21], v[30:31], v[20:21], s[38:39] op_sel_hi:[1,1,0]
	v_cmp_gt_f32_e32 vcc, 0, v16
	v_pk_mul_f32 v[20:21], v[30:31], v[20:21]
	v_and_b32_e32 v31, 0x7fffffff, v19
	v_and_b32_e32 v30, 0x7fffffff, v18
	v_pk_fma_f32 v[30:31], v[30:31], s[26:27], 1.0 op_sel_hi:[1,0,0]
	v_pk_mul_f32 v[20:21], v[22:23], v[20:21]
	v_rcp_f32_e32 v30, v30
	v_rcp_f32_e32 v31, v31
	v_pk_mul_f32 v[22:23], v[16:17], v[20:21]
	v_pk_fma_f32 v[20:21], v[16:17], v[20:21], v[16:17] neg_lo:[1,0,0] neg_hi:[1,0,0]
	v_pk_mul_f32 v[26:27], v[18:19], v[18:19]
	v_cndmask_b32_e32 v22, v20, v22, vcc
	v_cmp_gt_f32_e32 vcc, 0, v17
	v_pk_fma_f32 v[16:17], v[30:31], s[28:29], v[24:25] op_sel_hi:[1,0,0]
	s_nop 0
	v_cndmask_b32_e32 v23, v21, v23, vcc
	v_pk_mul_f32 v[20:21], v[26:27], s[40:41] op_sel_hi:[1,0]
	v_pk_fma_f32 v[16:17], v[30:31], v[16:17], s[34:35] op_sel_hi:[1,1,0]
	v_exp_f32_e32 v20, v20
	v_exp_f32_e32 v21, v21
	v_pk_fma_f32 v[16:17], v[30:31], v[16:17], s[36:37] op_sel_hi:[1,1,0]
	v_cmp_gt_f32_e32 vcc, 0, v18
	v_pk_fma_f32 v[16:17], v[30:31], v[16:17], s[38:39] op_sel_hi:[1,1,0]
	s_nop 0
	v_pk_mul_f32 v[16:17], v[30:31], v[16:17]
	s_nop 0
	v_pk_mul_f32 v[16:17], v[20:21], v[16:17]
	s_nop 0
	v_pk_mul_f32 v[20:21], v[18:19], v[16:17]
	v_pk_fma_f32 v[16:17], v[18:19], v[16:17], v[18:19] neg_lo:[1,0,0] neg_hi:[1,0,0]
	s_nop 0
	v_cndmask_b32_e32 v20, v16, v20, vcc
	v_cmp_gt_f32_e32 vcc, 0, v19
	v_cvt_pk_bf16_f32 v16, v34, v35
	s_nop 1
	v_cndmask_b32_e32 v19, v17, v21, vcc
	s_and_b64 vcc, exec, s[8:9]
	v_cvt_pk_bf16_f32 v17, v36, v37
	v_cvt_pk_bf16_f32 v18, v22, v23
	v_cvt_pk_bf16_f32 v19, v20, v19
	global_store_dwordx4 v[32:33], v[16:19], off offset:256
	s_cbranch_vccnz .LBB0_265
	v_lshlrev_b32_e32 v20, 16, v16
	v_and_b32_e32 v16, 0xffff0000, v16
	v_lshlrev_b32_e32 v22, 16, v17
	v_and_b32_e32 v24, 0xffff0000, v17
	v_lshlrev_b32_e32 v26, 16, v18
	v_and_b32_e32 v18, 0xffff0000, v18
	v_lshlrev_b32_e32 v30, 16, v19
	v_and_b32_e32 v32, 0xffff0000, v19
	v_mul_f32_e32 v21, v20, v20
	v_mul_f32_e32 v17, v16, v16
	v_mul_f32_e32 v23, v22, v22
	v_mul_f32_e32 v25, v24, v24
	v_mul_f32_e32 v27, v26, v26
	v_mul_f32_e32 v19, v18, v18
	v_mul_f32_e32 v31, v30, v30
	v_mul_f32_e32 v33, v32, v32
	v_pk_add_f32 v[16:17], v[20:21], v[16:17]
	v_pk_add_f32 v[20:21], v[22:23], v[24:25]
	v_pk_add_f32 v[18:19], v[26:27], v[18:19]
	v_pk_add_f32 v[16:17], v[16:17], v[20:21]
	v_pk_add_f32 v[20:21], v[30:31], v[32:33]
	s_nop 0
	v_pk_add_f32 v[18:19], v[18:19], v[20:21]
	s_nop 0
	v_pk_add_f32 v[16:17], v[16:17], v[18:19]
	s_nop 0
	v_pk_add_f32 v[16:17], v[28:29], v[16:17]
	s_nop 0
	v_mov_b32_e32 v18, v16
	v_mov_b32_e32 v19, v17
	s_nop 0
	v_permlane16_swap_b32_e32 v16, v18
	v_permlane16_swap_b32_e32 v17, v19
	v_pk_add_f32 v[16:17], v[16:17], v[18:19]
	s_nop 0
	v_mov_b32_e32 v18, v16
	v_mov_b32_e32 v19, v17
	s_nop 0
	v_permlane32_swap_b32_e32 v16, v18
	v_permlane32_swap_b32_e32 v17, v19
	v_pk_add_f32 v[16:17], v[16:17], v[18:19]
	s_and_saveexec_b64 s[10:11], s[4:5]
	s_cbranch_execz .LBB0_264
	v_lshlrev_b64 v[20:21], 8, v[150:151]
	v_lshl_add_u64 v[20:21], s[16:17], 0, v[20:21]
	v_lshl_add_u64 v[20:21], s[50:51], 2, v[20:21]
	global_store_dwordx2 v[20:21], v[16:17], off

.LBB0_267:
	v_mov_b32_e32 v19, v18
	v_pk_mul_f32 v[4:5], v[4:5], v[18:19]
	v_mov_b32_e32 v8, v18
	v_and_b32_e32 v11, 0x7fffffff, v5
	v_and_b32_e32 v10, 0x7fffffff, v4
	v_pk_fma_f32 v[10:11], v[10:11], s[26:27], 1.0 op_sel_hi:[1,0,0]
	v_mov_b32_e32 v9, v18
	v_rcp_f32_e32 v10, v10
	v_rcp_f32_e32 v11, v11
	v_pk_mul_f32 v[6:7], v[6:7], v[8:9]
	v_pk_mul_f32 v[2:3], v[2:3], v[8:9]
	v_pk_mul_f32 v[0:1], v[0:1], v[18:19]
	v_mov_b64_e32 v[8:9], s[30:31]
	v_pk_mul_f32 v[18:19], v[4:5], v[4:5]
	v_pk_fma_f32 v[14:15], v[10:11], s[28:29], v[8:9] op_sel_hi:[1,0,0]
	v_pk_mul_f32 v[18:19], v[18:19], s[40:41] op_sel_hi:[1,0]
	v_pk_fma_f32 v[14:15], v[10:11], v[14:15], s[34:35] op_sel_hi:[1,1,0]
	v_exp_f32_e32 v18, v18
	v_exp_f32_e32 v19, v19
	v_pk_fma_f32 v[14:15], v[10:11], v[14:15], s[36:37] op_sel_hi:[1,1,0]
	v_and_b32_e32 v21, 0x7fffffff, v7
	v_and_b32_e32 v20, 0x7fffffff, v6
	v_pk_fma_f32 v[14:15], v[10:11], v[14:15], s[38:39] op_sel_hi:[1,1,0]
	v_pk_fma_f32 v[20:21], v[20:21], s[26:27], 1.0 op_sel_hi:[1,0,0]
	v_pk_mul_f32 v[10:11], v[10:11], v[14:15]
	v_rcp_f32_e32 v20, v20
	v_rcp_f32_e32 v21, v21
	v_pk_mul_f32 v[10:11], v[18:19], v[10:11]
	v_cmp_gt_f32_e32 vcc, 0, v4
	v_pk_mul_f32 v[18:19], v[4:5], v[10:11]
	v_pk_fma_f32 v[10:11], v[4:5], v[10:11], v[4:5] neg_lo:[1,0,0] neg_hi:[1,0,0]
	v_pk_mul_f32 v[14:15], v[6:7], v[6:7]
	v_cndmask_b32_e32 v18, v10, v18, vcc
	v_cmp_gt_f32_e32 vcc, 0, v5
	v_pk_fma_f32 v[4:5], v[20:21], s[28:29], v[8:9] op_sel_hi:[1,0,0]
	s_nop 0
	v_cndmask_b32_e32 v19, v11, v19, vcc
	v_pk_mul_f32 v[10:11], v[14:15], s[40:41] op_sel_hi:[1,0]
	v_pk_fma_f32 v[4:5], v[20:21], v[4:5], s[34:35] op_sel_hi:[1,1,0]
	v_exp_f32_e32 v10, v10
	v_exp_f32_e32 v11, v11
	v_pk_fma_f32 v[4:5], v[20:21], v[4:5], s[36:37] op_sel_hi:[1,1,0]
	v_and_b32_e32 v15, 0x7fffffff, v1
	v_and_b32_e32 v14, 0x7fffffff, v0
	v_pk_fma_f32 v[4:5], v[20:21], v[4:5], s[38:39] op_sel_hi:[1,1,0]
	v_pk_fma_f32 v[14:15], v[14:15], s[26:27], 1.0 op_sel_hi:[1,0,0]
	v_pk_mul_f32 v[4:5], v[20:21], v[4:5]
	v_rcp_f32_e32 v14, v14
	v_rcp_f32_e32 v15, v15
	v_pk_mul_f32 v[4:5], v[10:11], v[4:5]
	v_cmp_gt_f32_e32 vcc, 0, v6
	v_pk_mul_f32 v[10:11], v[6:7], v[4:5]
	v_pk_fma_f32 v[4:5], v[6:7], v[4:5], v[6:7] neg_lo:[1,0,0] neg_hi:[1,0,0]
	s_nop 0
	v_cndmask_b32_e32 v20, v4, v10, vcc
	v_cmp_gt_f32_e32 vcc, 0, v7
	v_pk_mul_f32 v[6:7], v[0:1], v[0:1]
	s_nop 0
	v_cndmask_b32_e32 v21, v5, v11, vcc
	v_pk_fma_f32 v[4:5], v[14:15], s[28:29], v[8:9] op_sel_hi:[1,0,0]
	v_pk_mul_f32 v[6:7], v[6:7], s[40:41] op_sel_hi:[1,0]
	v_pk_fma_f32 v[4:5], v[14:15], v[4:5], s[34:35] op_sel_hi:[1,1,0]
	v_exp_f32_e32 v6, v6
	v_pk_fma_f32 v[4:5], v[14:15], v[4:5], s[36:37] op_sel_hi:[1,1,0]
	v_exp_f32_e32 v7, v7
	v_pk_fma_f32 v[4:5], v[14:15], v[4:5], s[38:39] op_sel_hi:[1,1,0]
	v_cmp_gt_f32_e32 vcc, 0, v0
	v_pk_mul_f32 v[4:5], v[14:15], v[4:5]
	v_and_b32_e32 v15, 0x7fffffff, v3
	v_and_b32_e32 v14, 0x7fffffff, v2
	v_pk_fma_f32 v[14:15], v[14:15], s[26:27], 1.0 op_sel_hi:[1,0,0]
	v_pk_mul_f32 v[4:5], v[6:7], v[4:5]
	v_rcp_f32_e32 v14, v14
	v_rcp_f32_e32 v15, v15
	v_pk_mul_f32 v[6:7], v[0:1], v[4:5]
	v_pk_fma_f32 v[4:5], v[0:1], v[4:5], v[0:1] neg_lo:[1,0,0] neg_hi:[1,0,0]
	v_pk_mul_f32 v[10:11], v[2:3], v[2:3]
	v_cndmask_b32_e32 v6, v4, v6, vcc
	v_cmp_gt_f32_e32 vcc, 0, v1
	v_pk_fma_f32 v[0:1], v[14:15], s[28:29], v[8:9] op_sel_hi:[1,0,0]
	s_nop 0
	v_cndmask_b32_e32 v7, v5, v7, vcc
	v_pk_mul_f32 v[4:5], v[10:11], s[40:41] op_sel_hi:[1,0]
	v_pk_fma_f32 v[0:1], v[14:15], v[0:1], s[34:35] op_sel_hi:[1,1,0]
	v_exp_f32_e32 v4, v4
	v_exp_f32_e32 v5, v5
	v_pk_fma_f32 v[0:1], v[14:15], v[0:1], s[36:37] op_sel_hi:[1,1,0]
	v_cmp_gt_f32_e32 vcc, 0, v2
	v_pk_fma_f32 v[0:1], v[14:15], v[0:1], s[38:39] op_sel_hi:[1,1,0]
	s_nop 0
	v_pk_mul_f32 v[0:1], v[14:15], v[0:1]
	s_nop 0
	v_pk_mul_f32 v[0:1], v[4:5], v[0:1]
	s_nop 0
	v_pk_mul_f32 v[4:5], v[2:3], v[0:1]
	v_pk_fma_f32 v[0:1], v[2:3], v[0:1], v[2:3] neg_lo:[1,0,0] neg_hi:[1,0,0]
	s_nop 0
	v_cndmask_b32_e32 v4, v0, v4, vcc
	v_cmp_gt_f32_e32 vcc, 0, v3
	v_cvt_pk_bf16_f32 v0, v18, v19
	s_nop 1
	v_cndmask_b32_e32 v3, v1, v5, vcc
	s_and_b64 vcc, exec, s[8:9]
	v_cvt_pk_bf16_f32 v1, v20, v21
	v_cvt_pk_bf16_f32 v2, v6, v7
	v_cvt_pk_bf16_f32 v3, v4, v3
	global_store_dwordx4 v[16:17], v[0:3], off offset:256
	s_cbranch_vccnz .LBB0_271
	v_lshlrev_b32_e32 v4, 16, v0
	v_and_b32_e32 v0, 0xffff0000, v0
	v_lshlrev_b32_e32 v6, 16, v1
	v_and_b32_e32 v8, 0xffff0000, v1
	v_lshlrev_b32_e32 v10, 16, v2
	v_and_b32_e32 v2, 0xffff0000, v2
	v_lshlrev_b32_e32 v14, 16, v3
	v_and_b32_e32 v16, 0xffff0000, v3
	v_mul_f32_e32 v5, v4, v4
	v_mul_f32_e32 v1, v0, v0
	v_mul_f32_e32 v7, v6, v6
	v_mul_f32_e32 v9, v8, v8
	v_mul_f32_e32 v11, v10, v10
	v_mul_f32_e32 v3, v2, v2
	v_mul_f32_e32 v15, v14, v14
	v_mul_f32_e32 v17, v16, v16
	v_pk_add_f32 v[0:1], v[4:5], v[0:1]
	v_pk_add_f32 v[4:5], v[6:7], v[8:9]
	v_pk_add_f32 v[2:3], v[10:11], v[2:3]
	v_pk_add_f32 v[0:1], v[0:1], v[4:5]
	v_pk_add_f32 v[4:5], v[14:15], v[16:17]
	s_nop 0
	v_pk_add_f32 v[2:3], v[2:3], v[4:5]
	s_nop 0
	v_pk_add_f32 v[0:1], v[0:1], v[2:3]
	s_nop 0
	v_pk_add_f32 v[0:1], v[12:13], v[0:1]
	s_nop 0
	v_mov_b32_e32 v2, v0
	v_mov_b32_e32 v3, v1
	s_nop 0
	v_permlane16_swap_b32_e32 v0, v2
	v_permlane16_swap_b32_e32 v1, v3
	v_pk_add_f32 v[0:1], v[0:1], v[2:3]
	s_nop 0
	v_mov_b32_e32 v2, v0
	v_mov_b32_e32 v3, v1
	s_nop 0
	v_permlane32_swap_b32_e32 v0, v2
	v_permlane32_swap_b32_e32 v1, v3
	v_pk_add_f32 v[0:1], v[0:1], v[2:3]
	s_and_saveexec_b64 s[8:9], s[4:5]
	s_cbranch_execz .LBB0_270
	v_lshlrev_b64 v[4:5], 8, v[148:149]
	v_lshl_add_u64 v[4:5], s[16:17], 0, v[4:5]
	v_lshl_add_u64 v[4:5], s[50:51], 2, v[4:5]
	global_store_dwordx2 v[4:5], v[0:1], off
